# sample-attention loop slimming 3: rope-key sum of squares written unmasked with a DPP add, tile-load base kept in scalar registers across tiles, invariant LDS destination reused
# baseline (speedup 1.0000x reference)
; DI void attn_sample_phase(const Args& a, LAS unsigned char* lds, int vcu, int G, int tid, int lane, int wave) {
;     ...
;         f32x2 rcur = *(const f32x2*)(rc + (split * 4096 + krow) * 16 + 2 * kp), rsur = *(const f32x2*)(rs + (split * 4096 + krow) * 16 + 2 * kp);
;         __syncthreads();
;         SA_LOAD(0, a0, a1, a2, a3, aka, akb);
;         SA_CONVERT(0, 0, a0, a1, a2, a3, aka, akb);
;         SA_LOAD(1, a0, a1, a2, a3, aka, akb);
;         __syncthreads();
;         f32x16 accT = {}; float lsum = 0.f; int c3 = 0;
; #pragma unroll 1
;         for (int j = 0; j < 128; ++j) {
.LBB0_900:
	s_or_b64 exec, exec, s[18:19]
	v_mov_b32_e32 v4, v3
	v_mov_b32_e32 v5, v3
	v_mov_b32_e32 v6, v3
	v_mov_b32_e32 v7, v3
	v_mov_b32_e32 v8, v3
	v_mov_b32_e32 v9, v3
	v_mov_b32_e32 v10, v3
	v_mov_b32_e32 v11, v3
	v_mov_b32_e32 v12, v3
	v_mov_b32_e32 v13, v3
	v_mov_b32_e32 v14, v3
	v_mov_b32_e32 v15, v3
	v_mov_b32_e32 v16, v3
	v_mov_b32_e32 v17, v3
	v_mov_b32_e32 v2, v3
	v_mov_b64_e32 v[18:19], v[16:17]
	s_mov_b32 s17, 0
	v_mov_b32_e32 v211, 0
	s_mov_b32 s24, 64
	s_mov_b32 s25, 2
	v_mov_b64_e32 v[16:17], v[14:15]
	v_mov_b64_e32 v[14:15], v[12:13]
	v_mov_b64_e32 v[12:13], v[10:11]
	v_mov_b64_e32 v[10:11], v[8:9]
	v_mov_b64_e32 v[8:9], v[6:7]
	v_mov_b64_e32 v[6:7], v[4:5]
	v_mov_b64_e32 v[4:5], v[2:3]
	v_readfirstlane_b32 s100, v166
	v_readfirstlane_b32 s101, v167
	v_readfirstlane_b32 s99, v158
	v_lshrrev_b32_e32 v255, 5, v142
	v_lshlrev_b32_e32 v255, 6, v255
	v_lshl_add_u32 v255, v140, 2, v255
	s_lshl_b32 s99, s99, 7
	v_lshl_add_u32 v255, v158, 7, v255
	v_add_u32_e32 v255, 0x17600, v255
	s_waitcnt lgkmcnt(0)
	s_barrier
	s_branch .LBB0_902

.Lsa_a4:
	s_add_i32 s18, s17, 1
	s_cmp_lg_u32 s17, 2
	s_cselect_b32 s17, s18, 0
	s_cmpk_eq_i32 s25, 0x81
	s_cbranch_scc1 .Lsa_a4end
	s_add_i32 s18, s25, -1
	s_and_b32 s28, s18, 1
	s_mul_i32 s27, s17, 0x4a00
	s_mul_i32 s18, s28, 0x2200
	v_add3_u32 v216, s18, v184, v180
	v_add_u32_e32 v217, s27, v183
	s_waitcnt vmcnt(3)
	v_cvt_pk_fp8_f32 v212, v120, v121
	v_cvt_pk_bf16_f32 v214, v120, v121
	v_cvt_pk_fp8_f32 v212, v122, v123 op_sel:[0,0,1]
	v_cvt_pk_bf16_f32 v215, v122, v123
	ds_write_b64 v217, v[214:215]
	ds_write_b32 v216, v212 offset:56832
	s_waitcnt vmcnt(2)
	v_cvt_pk_fp8_f32 v213, v124, v125
	v_cvt_pk_bf16_f32 v218, v124, v125
	v_cvt_pk_fp8_f32 v213, v126, v127 op_sel:[0,0,1]
	v_cvt_pk_bf16_f32 v219, v126, v127
	ds_write_b64 v217, v[218:219] offset:4736
	ds_write_b32 v216, v213 offset:59008
	s_waitcnt vmcnt(1)
	v_cvt_pk_fp8_f32 v212, v128, v129
	v_cvt_pk_bf16_f32 v214, v128, v129
	v_cvt_pk_fp8_f32 v212, v130, v131 op_sel:[0,0,1]
	v_cvt_pk_bf16_f32 v215, v130, v131
	ds_write_b64 v217, v[214:215] offset:9472
	ds_write_b32 v216, v212 offset:61184
	s_waitcnt vmcnt(0)
	v_cvt_pk_fp8_f32 v213, v132, v133
	v_cvt_pk_bf16_f32 v218, v132, v133
	v_cvt_pk_fp8_f32 v213, v134, v135 op_sel:[0,0,1]
	v_cvt_pk_bf16_f32 v219, v134, v135
	ds_write_b64 v217, v[218:219] offset:14208
	ds_write_b32 v216, v213 offset:63360
	s_and_saveexec_b64 s[18:19], s[2:3]
	s_cbranch_execz .LBB0_915
	v_pk_mul_f32 v[212:213], v[172:173], v[172:173]
	v_pk_mul_f32 v[214:215], v[174:175], v[174:175]
	v_add_f32_e32 v212, v212, v213
	v_add_f32_e32 v2, v214, v215
	v_add_f32_e32 v2, v212, v2
	s_nop 1
	v_add_f32_dpp v2, v2, v2 quad_perm:[1,0,3,2] row_mask:0xf bank_mask:0xf bound_ctrl:1
	s_nop 1
	v_add_f32_dpp v2, v2, v2 quad_perm:[2,3,0,1] row_mask:0xf bank_mask:0xf bound_ctrl:1
	s_nop 1
	v_add_f32_dpp v2, v2, v2 row_half_mirror row_mask:0xf bank_mask:0xf bound_ctrl:1
	v_lshl_add_u32 v212, s28, 7, v191
	ds_write_b32 v212, v2
	v_pk_mul_f32 v[214:215], v[146:147], v[174:175]
	v_pk_mul_f32 v[212:213], v[144:145], v[172:173]
	v_pk_mul_f32 v[216:217], v[214:215], v[178:179]
	s_nop 0
	v_pk_fma_f32 v[216:217], v[212:213], v[176:177], v[216:217] neg_lo:[0,0,1] neg_hi:[0,0,1]
	v_pk_mul_f32 v[212:213], v[212:213], v[178:179]
	v_cvt_pk_bf16_f32 v2, v216, v217
	v_pk_fma_f32 v[212:213], v[176:177], v[214:215], v[212:213]
	v_add3_u32 v214, s27, v192, v1
	v_cvt_pk_bf16_f32 v212, v212, v213
	ds_write2_b32 v214, v2, v212 offset0:128 offset1:136
	v_pk_mul_f32 v[212:213], v[150:151], v[178:179]
	v_pk_mul_f32 v[178:179], v[148:149], v[178:179]
	v_pk_fma_f32 v[212:213], v[148:149], v[176:177], v[212:213] neg_lo:[0,0,1] neg_hi:[0,0,1]
	v_pk_fma_f32 v[178:179], v[150:151], v[176:177], v[178:179]
	v_mov_b64_e32 v[176:177], v[212:213]
.LBB0_915:
	s_or_b64 exec, exec, s[18:19]
	s_cmpk_gt_u32 s26, 0x7d
	s_cbranch_scc1 .Lsa_a4end
	s_and_b32 s18, s25, -4
	s_add_i32 s18, s18, 0x17b80
	v_mov_b32_e32 v2, s18
	ds_read_b32 v2, v2
	s_and_b32 s20, s24, 0x60
	v_lshlrev_b32_e32 v212, 4, v0
	s_waitcnt lgkmcnt(0)
	v_readfirstlane_b32 s18, v2
	s_ashr_i32 s19, s18, 31
	s_lshl_b64 s[18:19], s[18:19], 7
	s_or_b32 s18, s18, s20
	s_lshl_b64 s[20:21], s[18:19], 10
	s_add_u32 s20, s20, s100
	s_addc_u32 s21, s21, s101
	global_load_dwordx4 v[120:123], v212, s[20:21] nt
	s_add_u32 s20, s20, 0x2000
	s_addc_u32 s21, s21, 0
	global_load_dwordx4 v[124:127], v212, s[20:21] nt
	s_add_u32 s20, s20, 0x2000
	s_addc_u32 s21, s21, 0
	global_load_dwordx4 v[128:131], v212, s[20:21] nt
	s_add_u32 s20, s20, 0x2000
	s_addc_u32 s21, s21, 0
	global_load_dwordx4 v[132:135], v212, s[20:21] nt
	s_and_saveexec_b64 s[20:21], s[2:3]
	s_cbranch_execz .LBB0_918
	v_mov_b32_e32 v173, s19
	v_or_b32_e32 v172, s18, v160
	v_lshlrev_b64 v[172:173], 7, v[172:173]
	v_lshl_add_u64 v[174:175], v[156:157], 0, v[172:173]
	global_load_dwordx2 v[172:173], v[174:175], off nt
	s_nop 0
	global_load_dwordx2 v[174:175], v[174:175], off offset:64 nt
